# P1 epilogue: sigmoid/silu chunk math regenerated with packed mul/add (constants in SGPRs), k-section path specialised; attention bias init scalar
# baseline (speedup 1.0000x reference)
.Lmy_e1_act1:
	s_mov_b32 s98, 0xbfb8aa3b
	s_mov_b32 s100, 1.0
	s_xor_b64 s[74:75], s[74:75], -1
	s_mov_b64 s[78:79], -1
	s_xor_b64 s[76:77], s[76:77], -1
	v_pk_mul_f32 v[200:201], v[122:123], s[98:99] op_sel_hi:[1,0]
	v_pk_mul_f32 v[202:203], v[124:125], s[98:99] op_sel_hi:[1,0]
	v_pk_mul_f32 v[204:205], v[126:127], s[98:99] op_sel_hi:[1,0]
	v_pk_mul_f32 v[206:207], v[128:129], s[98:99] op_sel_hi:[1,0]
	v_exp_f32_e32 v200, v200
	v_exp_f32_e32 v201, v201
	v_exp_f32_e32 v202, v202
	v_exp_f32_e32 v203, v203
	v_exp_f32_e32 v204, v204
	v_exp_f32_e32 v205, v205
	v_exp_f32_e32 v206, v206
	v_exp_f32_e32 v207, v207
	v_pk_add_f32 v[200:201], v[200:201], s[100:101] op_sel_hi:[1,0]
	v_pk_add_f32 v[202:203], v[202:203], s[100:101] op_sel_hi:[1,0]
	v_pk_add_f32 v[204:205], v[204:205], s[100:101] op_sel_hi:[1,0]
	v_pk_add_f32 v[206:207], v[206:207], s[100:101] op_sel_hi:[1,0]
	v_rcp_f32_e32 v200, v200
	v_rcp_f32_e32 v201, v201
	v_rcp_f32_e32 v202, v202
	v_rcp_f32_e32 v203, v203
	v_rcp_f32_e32 v204, v204
	v_rcp_f32_e32 v205, v205
	v_rcp_f32_e32 v206, v206
	v_rcp_f32_e32 v207, v207
	v_pk_mul_f32 v[200:201], v[122:123], v[200:201]
	v_pk_mul_f32 v[202:203], v[124:125], v[202:203]
	v_pk_mul_f32 v[204:205], v[126:127], v[204:205]
	v_pk_mul_f32 v[206:207], v[128:129], v[206:207]
	v_mov_b32_e32 v162, 0
	s_lshl_b32 s6, s6, 8
	s_add_i32 s6, s7, s6
	v_or_b32_e32 v122, s6, v156
	s_lshl_b32 s6, s72, 1
	s_add_u32 s6, s38, s6
	v_lshl_add_u32 v161, s8, 8, v154
	s_addc_u32 s7, s39, 0
	v_ashrrev_i32_e32 v123, 31, v122
	v_lshl_add_u64 v[122:123], v[122:123], 1, s[6:7]
	v_mad_i64_i32 v[124:125], s[6:7], s70, v161, 0
	v_lshl_add_u64 v[124:125], v[124:125], 1, v[122:123]
	v_cvt_pk_bf16_f32 v126, v204, v205
	v_cvt_pk_bf16_f32 v127, v206, v207
	v_cvt_pk_bf16_f32 v128, v200, v201
	v_cvt_pk_bf16_f32 v129, v202, v203
	global_store_dwordx4 v[124:125], v[126:129], off
	s_nop 1
	v_cndmask_b32_e64 v126, 0, 1, s[76:77]
	v_cmp_ne_u32_e64 s[6:7], 1, v126
	v_pk_mul_f32 v[200:201], v[114:115], s[98:99] op_sel_hi:[1,0]
	v_pk_mul_f32 v[202:203], v[116:117], s[98:99] op_sel_hi:[1,0]
	v_pk_mul_f32 v[204:205], v[118:119], s[98:99] op_sel_hi:[1,0]
	v_pk_mul_f32 v[206:207], v[120:121], s[98:99] op_sel_hi:[1,0]
	v_exp_f32_e32 v200, v200
	v_exp_f32_e32 v201, v201
	v_exp_f32_e32 v202, v202
	v_exp_f32_e32 v203, v203
	v_exp_f32_e32 v204, v204
	v_exp_f32_e32 v205, v205
	v_exp_f32_e32 v206, v206
	v_exp_f32_e32 v207, v207
	v_pk_add_f32 v[200:201], v[200:201], s[100:101] op_sel_hi:[1,0]
	v_pk_add_f32 v[202:203], v[202:203], s[100:101] op_sel_hi:[1,0]
	v_pk_add_f32 v[204:205], v[204:205], s[100:101] op_sel_hi:[1,0]
	v_pk_add_f32 v[206:207], v[206:207], s[100:101] op_sel_hi:[1,0]
	v_rcp_f32_e32 v200, v200
	v_rcp_f32_e32 v201, v201
	v_rcp_f32_e32 v202, v202
	v_rcp_f32_e32 v203, v203
	v_rcp_f32_e32 v204, v204
	v_rcp_f32_e32 v205, v205
	v_rcp_f32_e32 v206, v206
	v_rcp_f32_e32 v207, v207
	v_pk_mul_f32 v[200:201], v[114:115], v[200:201]
	v_pk_mul_f32 v[202:203], v[116:117], v[202:203]
	v_pk_mul_f32 v[204:205], v[118:119], v[204:205]
	v_pk_mul_f32 v[206:207], v[120:121], v[206:207]
	v_mov_b32_e32 v150, v162
	v_cvt_pk_bf16_f32 v114, v204, v205
	v_cvt_pk_bf16_f32 v115, v206, v207
	v_cvt_pk_bf16_f32 v116, v200, v201
	v_cvt_pk_bf16_f32 v117, v202, v203
	global_store_dwordx4 v[124:125], v[114:117], off offset:256
	v_pk_mul_f32 v[200:201], v[106:107], s[98:99] op_sel_hi:[1,0]
	v_pk_mul_f32 v[202:203], v[108:109], s[98:99] op_sel_hi:[1,0]
	v_pk_mul_f32 v[204:205], v[110:111], s[98:99] op_sel_hi:[1,0]
	v_pk_mul_f32 v[206:207], v[112:113], s[98:99] op_sel_hi:[1,0]
	v_exp_f32_e32 v200, v200
	v_exp_f32_e32 v201, v201
	v_exp_f32_e32 v202, v202
	v_exp_f32_e32 v203, v203
	v_exp_f32_e32 v204, v204
	v_exp_f32_e32 v205, v205
	v_exp_f32_e32 v206, v206
	v_exp_f32_e32 v207, v207
	v_pk_add_f32 v[200:201], v[200:201], s[100:101] op_sel_hi:[1,0]
	v_pk_add_f32 v[202:203], v[202:203], s[100:101] op_sel_hi:[1,0]
	v_pk_add_f32 v[204:205], v[204:205], s[100:101] op_sel_hi:[1,0]
	v_pk_add_f32 v[206:207], v[206:207], s[100:101] op_sel_hi:[1,0]
	v_rcp_f32_e32 v200, v200
	v_rcp_f32_e32 v201, v201
	v_rcp_f32_e32 v202, v202
	v_rcp_f32_e32 v203, v203
	v_rcp_f32_e32 v204, v204
	v_rcp_f32_e32 v205, v205
	v_rcp_f32_e32 v206, v206
	v_rcp_f32_e32 v207, v207
	v_pk_mul_f32 v[200:201], v[106:107], v[200:201]
	v_pk_mul_f32 v[202:203], v[108:109], v[202:203]
	v_pk_mul_f32 v[204:205], v[110:111], v[204:205]
	v_pk_mul_f32 v[206:207], v[112:113], v[206:207]
	v_mov_b32_e32 v124, v150
	v_or_b32_e32 v106, 16, v161
	v_mad_i64_i32 v[106:107], s[72:73], s70, v106, 0
	v_lshl_add_u64 v[106:107], v[106:107], 1, v[122:123]
	v_cvt_pk_bf16_f32 v108, v204, v205
	v_cvt_pk_bf16_f32 v109, v206, v207
	v_cvt_pk_bf16_f32 v110, v200, v201
	v_cvt_pk_bf16_f32 v111, v202, v203
	global_store_dwordx4 v[106:107], v[108:111], off
	v_pk_mul_f32 v[200:201], v[98:99], s[98:99] op_sel_hi:[1,0]
	v_pk_mul_f32 v[202:203], v[100:101], s[98:99] op_sel_hi:[1,0]
	v_pk_mul_f32 v[204:205], v[102:103], s[98:99] op_sel_hi:[1,0]
	v_pk_mul_f32 v[206:207], v[104:105], s[98:99] op_sel_hi:[1,0]
	v_exp_f32_e32 v200, v200
	v_exp_f32_e32 v201, v201
	v_exp_f32_e32 v202, v202
	v_exp_f32_e32 v203, v203
	v_exp_f32_e32 v204, v204
	v_exp_f32_e32 v205, v205
	v_exp_f32_e32 v206, v206
	v_exp_f32_e32 v207, v207
	v_pk_add_f32 v[200:201], v[200:201], s[100:101] op_sel_hi:[1,0]
	v_pk_add_f32 v[202:203], v[202:203], s[100:101] op_sel_hi:[1,0]
	v_pk_add_f32 v[204:205], v[204:205], s[100:101] op_sel_hi:[1,0]
	v_pk_add_f32 v[206:207], v[206:207], s[100:101] op_sel_hi:[1,0]
	v_rcp_f32_e32 v200, v200
	v_rcp_f32_e32 v201, v201
	v_rcp_f32_e32 v202, v202
	v_rcp_f32_e32 v203, v203
	v_rcp_f32_e32 v204, v204
	v_rcp_f32_e32 v205, v205
	v_rcp_f32_e32 v206, v206
	v_rcp_f32_e32 v207, v207
	v_pk_mul_f32 v[200:201], v[98:99], v[200:201]
	v_pk_mul_f32 v[202:203], v[100:101], v[202:203]
	v_pk_mul_f32 v[204:205], v[102:103], v[204:205]
	v_pk_mul_f32 v[206:207], v[104:105], v[206:207]
	v_mov_b32_e32 v116, v124
	v_cvt_pk_bf16_f32 v98, v204, v205
	v_cvt_pk_bf16_f32 v99, v206, v207
	v_cvt_pk_bf16_f32 v100, v200, v201
	v_cvt_pk_bf16_f32 v101, v202, v203
	global_store_dwordx4 v[106:107], v[98:101], off offset:256
	v_pk_mul_f32 v[200:201], v[90:91], s[98:99] op_sel_hi:[1,0]
	v_pk_mul_f32 v[202:203], v[92:93], s[98:99] op_sel_hi:[1,0]
	v_pk_mul_f32 v[204:205], v[94:95], s[98:99] op_sel_hi:[1,0]
	v_pk_mul_f32 v[206:207], v[96:97], s[98:99] op_sel_hi:[1,0]
	v_exp_f32_e32 v200, v200
	v_exp_f32_e32 v201, v201
	v_exp_f32_e32 v202, v202
	v_exp_f32_e32 v203, v203
	v_exp_f32_e32 v204, v204
	v_exp_f32_e32 v205, v205
	v_exp_f32_e32 v206, v206
	v_exp_f32_e32 v207, v207
	v_pk_add_f32 v[200:201], v[200:201], s[100:101] op_sel_hi:[1,0]
	v_pk_add_f32 v[202:203], v[202:203], s[100:101] op_sel_hi:[1,0]
	v_pk_add_f32 v[204:205], v[204:205], s[100:101] op_sel_hi:[1,0]
	v_pk_add_f32 v[206:207], v[206:207], s[100:101] op_sel_hi:[1,0]
	v_rcp_f32_e32 v200, v200
	v_rcp_f32_e32 v201, v201
	v_rcp_f32_e32 v202, v202
	v_rcp_f32_e32 v203, v203
	v_rcp_f32_e32 v204, v204
	v_rcp_f32_e32 v205, v205
	v_rcp_f32_e32 v206, v206
	v_rcp_f32_e32 v207, v207
	v_pk_mul_f32 v[200:201], v[90:91], v[200:201]
	v_pk_mul_f32 v[202:203], v[92:93], v[202:203]
	v_pk_mul_f32 v[204:205], v[94:95], v[204:205]
	v_pk_mul_f32 v[206:207], v[96:97], v[206:207]
	v_mov_b32_e32 v106, v116
	v_or_b32_e32 v90, 32, v161
	v_mad_i64_i32 v[90:91], s[72:73], s70, v90, 0
	v_lshl_add_u64 v[90:91], v[90:91], 1, v[122:123]
	v_cvt_pk_bf16_f32 v92, v204, v205
	v_cvt_pk_bf16_f32 v93, v206, v207
	v_cvt_pk_bf16_f32 v94, v200, v201
	v_cvt_pk_bf16_f32 v95, v202, v203
	global_store_dwordx4 v[90:91], v[92:95], off
	v_pk_mul_f32 v[200:201], v[82:83], s[98:99] op_sel_hi:[1,0]
	v_pk_mul_f32 v[202:203], v[84:85], s[98:99] op_sel_hi:[1,0]
	v_pk_mul_f32 v[204:205], v[86:87], s[98:99] op_sel_hi:[1,0]
	v_pk_mul_f32 v[206:207], v[88:89], s[98:99] op_sel_hi:[1,0]
	v_exp_f32_e32 v200, v200
	v_exp_f32_e32 v201, v201
	v_exp_f32_e32 v202, v202
	v_exp_f32_e32 v203, v203
	v_exp_f32_e32 v204, v204
	v_exp_f32_e32 v205, v205
	v_exp_f32_e32 v206, v206
	v_exp_f32_e32 v207, v207
	v_pk_add_f32 v[200:201], v[200:201], s[100:101] op_sel_hi:[1,0]
	v_pk_add_f32 v[202:203], v[202:203], s[100:101] op_sel_hi:[1,0]
	v_pk_add_f32 v[204:205], v[204:205], s[100:101] op_sel_hi:[1,0]
	v_pk_add_f32 v[206:207], v[206:207], s[100:101] op_sel_hi:[1,0]
	v_rcp_f32_e32 v200, v200
	v_rcp_f32_e32 v201, v201
	v_rcp_f32_e32 v202, v202
	v_rcp_f32_e32 v203, v203
	v_rcp_f32_e32 v204, v204
	v_rcp_f32_e32 v205, v205
	v_rcp_f32_e32 v206, v206
	v_rcp_f32_e32 v207, v207
	v_pk_mul_f32 v[200:201], v[82:83], v[200:201]
	v_pk_mul_f32 v[202:203], v[84:85], v[202:203]
	v_pk_mul_f32 v[204:205], v[86:87], v[204:205]
	v_pk_mul_f32 v[206:207], v[88:89], v[206:207]
	v_mov_b32_e32 v100, v106
	v_cvt_pk_bf16_f32 v82, v204, v205
	v_cvt_pk_bf16_f32 v83, v206, v207
	v_cvt_pk_bf16_f32 v84, v200, v201
	v_cvt_pk_bf16_f32 v85, v202, v203
	global_store_dwordx4 v[90:91], v[82:85], off offset:256
	v_pk_mul_f32 v[200:201], v[74:75], s[98:99] op_sel_hi:[1,0]
	v_pk_mul_f32 v[202:203], v[76:77], s[98:99] op_sel_hi:[1,0]
	v_pk_mul_f32 v[204:205], v[78:79], s[98:99] op_sel_hi:[1,0]
	v_pk_mul_f32 v[206:207], v[80:81], s[98:99] op_sel_hi:[1,0]
	v_exp_f32_e32 v200, v200
	v_exp_f32_e32 v201, v201
	v_exp_f32_e32 v202, v202
	v_exp_f32_e32 v203, v203
	v_exp_f32_e32 v204, v204
	v_exp_f32_e32 v205, v205
	v_exp_f32_e32 v206, v206
	v_exp_f32_e32 v207, v207
	v_pk_add_f32 v[200:201], v[200:201], s[100:101] op_sel_hi:[1,0]
	v_pk_add_f32 v[202:203], v[202:203], s[100:101] op_sel_hi:[1,0]
	v_pk_add_f32 v[204:205], v[204:205], s[100:101] op_sel_hi:[1,0]
	v_pk_add_f32 v[206:207], v[206:207], s[100:101] op_sel_hi:[1,0]
	v_rcp_f32_e32 v200, v200
	v_rcp_f32_e32 v201, v201
	v_rcp_f32_e32 v202, v202
	v_rcp_f32_e32 v203, v203
	v_rcp_f32_e32 v204, v204
	v_rcp_f32_e32 v205, v205
	v_rcp_f32_e32 v206, v206
	v_rcp_f32_e32 v207, v207
	v_pk_mul_f32 v[200:201], v[74:75], v[200:201]
	v_pk_mul_f32 v[202:203], v[76:77], v[202:203]
	v_pk_mul_f32 v[204:205], v[78:79], v[204:205]
	v_pk_mul_f32 v[206:207], v[80:81], v[206:207]
	v_mov_b32_e32 v90, v100
	v_or_b32_e32 v74, 48, v161
	v_mad_i64_i32 v[74:75], s[72:73], s70, v74, 0
	v_lshl_add_u64 v[74:75], v[74:75], 1, v[122:123]
	v_cvt_pk_bf16_f32 v76, v204, v205
	v_cvt_pk_bf16_f32 v77, v206, v207
	v_cvt_pk_bf16_f32 v78, v200, v201
	v_cvt_pk_bf16_f32 v79, v202, v203
	global_store_dwordx4 v[74:75], v[76:79], off
	v_pk_mul_f32 v[200:201], v[66:67], s[98:99] op_sel_hi:[1,0]
	v_pk_mul_f32 v[202:203], v[68:69], s[98:99] op_sel_hi:[1,0]
	v_pk_mul_f32 v[204:205], v[70:71], s[98:99] op_sel_hi:[1,0]
	v_pk_mul_f32 v[206:207], v[72:73], s[98:99] op_sel_hi:[1,0]
	v_exp_f32_e32 v200, v200
	v_exp_f32_e32 v201, v201
	v_exp_f32_e32 v202, v202
	v_exp_f32_e32 v203, v203
	v_exp_f32_e32 v204, v204
	v_exp_f32_e32 v205, v205
	v_exp_f32_e32 v206, v206
	v_exp_f32_e32 v207, v207
	v_pk_add_f32 v[200:201], v[200:201], s[100:101] op_sel_hi:[1,0]
	v_pk_add_f32 v[202:203], v[202:203], s[100:101] op_sel_hi:[1,0]
	v_pk_add_f32 v[204:205], v[204:205], s[100:101] op_sel_hi:[1,0]
	v_pk_add_f32 v[206:207], v[206:207], s[100:101] op_sel_hi:[1,0]
	v_rcp_f32_e32 v200, v200
	v_rcp_f32_e32 v201, v201
	v_rcp_f32_e32 v202, v202
	v_rcp_f32_e32 v203, v203
	v_rcp_f32_e32 v204, v204
	v_rcp_f32_e32 v205, v205
	v_rcp_f32_e32 v206, v206
	v_rcp_f32_e32 v207, v207
	v_pk_mul_f32 v[200:201], v[66:67], v[200:201]
	v_pk_mul_f32 v[202:203], v[68:69], v[202:203]
	v_pk_mul_f32 v[204:205], v[70:71], v[204:205]
	v_pk_mul_f32 v[206:207], v[72:73], v[206:207]
	v_mov_b32_e32 v84, v90
	v_cvt_pk_bf16_f32 v66, v204, v205
	v_cvt_pk_bf16_f32 v67, v206, v207
	v_cvt_pk_bf16_f32 v68, v200, v201
	v_cvt_pk_bf16_f32 v69, v202, v203
	global_store_dwordx4 v[74:75], v[66:69], off offset:256
	v_pk_mul_f32 v[200:201], v[58:59], s[98:99] op_sel_hi:[1,0]
	v_pk_mul_f32 v[202:203], v[60:61], s[98:99] op_sel_hi:[1,0]
	v_pk_mul_f32 v[204:205], v[62:63], s[98:99] op_sel_hi:[1,0]
	v_pk_mul_f32 v[206:207], v[64:65], s[98:99] op_sel_hi:[1,0]
	v_exp_f32_e32 v200, v200
	v_exp_f32_e32 v201, v201
	v_exp_f32_e32 v202, v202
	v_exp_f32_e32 v203, v203
	v_exp_f32_e32 v204, v204
	v_exp_f32_e32 v205, v205
	v_exp_f32_e32 v206, v206
	v_exp_f32_e32 v207, v207
	v_pk_add_f32 v[200:201], v[200:201], s[100:101] op_sel_hi:[1,0]
	v_pk_add_f32 v[202:203], v[202:203], s[100:101] op_sel_hi:[1,0]
	v_pk_add_f32 v[204:205], v[204:205], s[100:101] op_sel_hi:[1,0]
	v_pk_add_f32 v[206:207], v[206:207], s[100:101] op_sel_hi:[1,0]
	v_rcp_f32_e32 v200, v200
	v_rcp_f32_e32 v201, v201
	v_rcp_f32_e32 v202, v202
	v_rcp_f32_e32 v203, v203
	v_rcp_f32_e32 v204, v204
	v_rcp_f32_e32 v205, v205
	v_rcp_f32_e32 v206, v206
	v_rcp_f32_e32 v207, v207
	v_pk_mul_f32 v[200:201], v[58:59], v[200:201]
	v_pk_mul_f32 v[202:203], v[60:61], v[202:203]
	v_pk_mul_f32 v[204:205], v[62:63], v[204:205]
	v_pk_mul_f32 v[206:207], v[64:65], v[206:207]
	v_mov_b32_e32 v74, v84
	v_add_u32_e32 v58, 0x80, v161
	v_mad_i64_i32 v[58:59], s[72:73], s70, v58, 0
	v_lshl_add_u64 v[58:59], v[58:59], 1, v[122:123]
	v_cvt_pk_bf16_f32 v60, v204, v205
	v_cvt_pk_bf16_f32 v61, v206, v207
	v_cvt_pk_bf16_f32 v62, v200, v201
	v_cvt_pk_bf16_f32 v63, v202, v203
	global_store_dwordx4 v[58:59], v[60:63], off
	v_pk_mul_f32 v[200:201], v[50:51], s[98:99] op_sel_hi:[1,0]
	v_pk_mul_f32 v[202:203], v[52:53], s[98:99] op_sel_hi:[1,0]
	v_pk_mul_f32 v[204:205], v[54:55], s[98:99] op_sel_hi:[1,0]
	v_pk_mul_f32 v[206:207], v[56:57], s[98:99] op_sel_hi:[1,0]
	v_exp_f32_e32 v200, v200
	v_exp_f32_e32 v201, v201
	v_exp_f32_e32 v202, v202
	v_exp_f32_e32 v203, v203
	v_exp_f32_e32 v204, v204
	v_exp_f32_e32 v205, v205
	v_exp_f32_e32 v206, v206
	v_exp_f32_e32 v207, v207
	v_pk_add_f32 v[200:201], v[200:201], s[100:101] op_sel_hi:[1,0]
	v_pk_add_f32 v[202:203], v[202:203], s[100:101] op_sel_hi:[1,0]
	v_pk_add_f32 v[204:205], v[204:205], s[100:101] op_sel_hi:[1,0]
	v_pk_add_f32 v[206:207], v[206:207], s[100:101] op_sel_hi:[1,0]
	v_rcp_f32_e32 v200, v200
	v_rcp_f32_e32 v201, v201
	v_rcp_f32_e32 v202, v202
	v_rcp_f32_e32 v203, v203
	v_rcp_f32_e32 v204, v204
	v_rcp_f32_e32 v205, v205
	v_rcp_f32_e32 v206, v206
	v_rcp_f32_e32 v207, v207
	v_pk_mul_f32 v[200:201], v[50:51], v[200:201]
	v_pk_mul_f32 v[202:203], v[52:53], v[202:203]
	v_pk_mul_f32 v[204:205], v[54:55], v[204:205]
	v_pk_mul_f32 v[206:207], v[56:57], v[206:207]
	v_mov_b32_e32 v68, v74
	v_cvt_pk_bf16_f32 v50, v204, v205
	v_cvt_pk_bf16_f32 v51, v206, v207
	v_cvt_pk_bf16_f32 v52, v200, v201
	v_cvt_pk_bf16_f32 v53, v202, v203
	global_store_dwordx4 v[58:59], v[50:53], off offset:256
	v_pk_mul_f32 v[200:201], v[42:43], s[98:99] op_sel_hi:[1,0]
	v_pk_mul_f32 v[202:203], v[44:45], s[98:99] op_sel_hi:[1,0]
	v_pk_mul_f32 v[204:205], v[46:47], s[98:99] op_sel_hi:[1,0]
	v_pk_mul_f32 v[206:207], v[48:49], s[98:99] op_sel_hi:[1,0]
	v_exp_f32_e32 v200, v200
	v_exp_f32_e32 v201, v201
	v_exp_f32_e32 v202, v202
	v_exp_f32_e32 v203, v203
	v_exp_f32_e32 v204, v204
	v_exp_f32_e32 v205, v205
	v_exp_f32_e32 v206, v206
	v_exp_f32_e32 v207, v207
	v_pk_add_f32 v[200:201], v[200:201], s[100:101] op_sel_hi:[1,0]
	v_pk_add_f32 v[202:203], v[202:203], s[100:101] op_sel_hi:[1,0]
	v_pk_add_f32 v[204:205], v[204:205], s[100:101] op_sel_hi:[1,0]
	v_pk_add_f32 v[206:207], v[206:207], s[100:101] op_sel_hi:[1,0]
	v_rcp_f32_e32 v200, v200
	v_rcp_f32_e32 v201, v201
	v_rcp_f32_e32 v202, v202
	v_rcp_f32_e32 v203, v203
	v_rcp_f32_e32 v204, v204
	v_rcp_f32_e32 v205, v205
	v_rcp_f32_e32 v206, v206
	v_rcp_f32_e32 v207, v207
	v_pk_mul_f32 v[200:201], v[42:43], v[200:201]
	v_pk_mul_f32 v[202:203], v[44:45], v[202:203]
	v_pk_mul_f32 v[204:205], v[46:47], v[204:205]
	v_pk_mul_f32 v[206:207], v[48:49], v[206:207]
	v_mov_b32_e32 v58, v68
	v_add_u32_e32 v42, 0x90, v161
	v_mad_i64_i32 v[42:43], s[72:73], s70, v42, 0
	v_lshl_add_u64 v[42:43], v[42:43], 1, v[122:123]
	v_cvt_pk_bf16_f32 v44, v204, v205
	v_cvt_pk_bf16_f32 v45, v206, v207
	v_cvt_pk_bf16_f32 v46, v200, v201
	v_cvt_pk_bf16_f32 v47, v202, v203
	global_store_dwordx4 v[42:43], v[44:47], off
	v_pk_mul_f32 v[200:201], v[34:35], s[98:99] op_sel_hi:[1,0]
	v_pk_mul_f32 v[202:203], v[36:37], s[98:99] op_sel_hi:[1,0]
	v_pk_mul_f32 v[204:205], v[38:39], s[98:99] op_sel_hi:[1,0]
	v_pk_mul_f32 v[206:207], v[40:41], s[98:99] op_sel_hi:[1,0]
	v_exp_f32_e32 v200, v200
	v_exp_f32_e32 v201, v201
	v_exp_f32_e32 v202, v202
	v_exp_f32_e32 v203, v203
	v_exp_f32_e32 v204, v204
	v_exp_f32_e32 v205, v205
	v_exp_f32_e32 v206, v206
	v_exp_f32_e32 v207, v207
	v_pk_add_f32 v[200:201], v[200:201], s[100:101] op_sel_hi:[1,0]
	v_pk_add_f32 v[202:203], v[202:203], s[100:101] op_sel_hi:[1,0]
	v_pk_add_f32 v[204:205], v[204:205], s[100:101] op_sel_hi:[1,0]
	v_pk_add_f32 v[206:207], v[206:207], s[100:101] op_sel_hi:[1,0]
	v_rcp_f32_e32 v200, v200
	v_rcp_f32_e32 v201, v201
	v_rcp_f32_e32 v202, v202
	v_rcp_f32_e32 v203, v203
	v_rcp_f32_e32 v204, v204
	v_rcp_f32_e32 v205, v205
	v_rcp_f32_e32 v206, v206
	v_rcp_f32_e32 v207, v207
	v_pk_mul_f32 v[200:201], v[34:35], v[200:201]
	v_pk_mul_f32 v[202:203], v[36:37], v[202:203]
	v_pk_mul_f32 v[204:205], v[38:39], v[204:205]
	v_pk_mul_f32 v[206:207], v[40:41], v[206:207]
	v_mov_b32_e32 v52, v58
	v_cvt_pk_bf16_f32 v34, v204, v205
	v_cvt_pk_bf16_f32 v35, v206, v207
	v_cvt_pk_bf16_f32 v36, v200, v201
	v_cvt_pk_bf16_f32 v37, v202, v203
	global_store_dwordx4 v[42:43], v[34:37], off offset:256
	v_pk_mul_f32 v[200:201], v[26:27], s[98:99] op_sel_hi:[1,0]
	v_pk_mul_f32 v[202:203], v[28:29], s[98:99] op_sel_hi:[1,0]
	v_pk_mul_f32 v[204:205], v[30:31], s[98:99] op_sel_hi:[1,0]
	v_pk_mul_f32 v[206:207], v[32:33], s[98:99] op_sel_hi:[1,0]
	v_exp_f32_e32 v200, v200
	v_exp_f32_e32 v201, v201
	v_exp_f32_e32 v202, v202
	v_exp_f32_e32 v203, v203
	v_exp_f32_e32 v204, v204
	v_exp_f32_e32 v205, v205
	v_exp_f32_e32 v206, v206
	v_exp_f32_e32 v207, v207
	v_pk_add_f32 v[200:201], v[200:201], s[100:101] op_sel_hi:[1,0]
	v_pk_add_f32 v[202:203], v[202:203], s[100:101] op_sel_hi:[1,0]
	v_pk_add_f32 v[204:205], v[204:205], s[100:101] op_sel_hi:[1,0]
	v_pk_add_f32 v[206:207], v[206:207], s[100:101] op_sel_hi:[1,0]
	v_rcp_f32_e32 v200, v200
	v_rcp_f32_e32 v201, v201
	v_rcp_f32_e32 v202, v202
	v_rcp_f32_e32 v203, v203
	v_rcp_f32_e32 v204, v204
	v_rcp_f32_e32 v205, v205
	v_rcp_f32_e32 v206, v206
	v_rcp_f32_e32 v207, v207
	v_pk_mul_f32 v[200:201], v[26:27], v[200:201]
	v_pk_mul_f32 v[202:203], v[28:29], v[202:203]
	v_pk_mul_f32 v[204:205], v[30:31], v[204:205]
	v_pk_mul_f32 v[206:207], v[32:33], v[206:207]
	v_mov_b32_e32 v42, v52
	v_add_u32_e32 v26, 0xa0, v161
	v_mad_i64_i32 v[26:27], s[72:73], s70, v26, 0
	v_lshl_add_u64 v[26:27], v[26:27], 1, v[122:123]
	v_cvt_pk_bf16_f32 v28, v204, v205
	v_cvt_pk_bf16_f32 v29, v206, v207
	v_cvt_pk_bf16_f32 v30, v200, v201
	v_cvt_pk_bf16_f32 v31, v202, v203
	global_store_dwordx4 v[26:27], v[28:31], off
	v_pk_mul_f32 v[200:201], v[18:19], s[98:99] op_sel_hi:[1,0]
	v_pk_mul_f32 v[202:203], v[20:21], s[98:99] op_sel_hi:[1,0]
	v_pk_mul_f32 v[204:205], v[22:23], s[98:99] op_sel_hi:[1,0]
	v_pk_mul_f32 v[206:207], v[24:25], s[98:99] op_sel_hi:[1,0]
	v_exp_f32_e32 v200, v200
	v_exp_f32_e32 v201, v201
	v_exp_f32_e32 v202, v202
	v_exp_f32_e32 v203, v203
	v_exp_f32_e32 v204, v204
	v_exp_f32_e32 v205, v205
	v_exp_f32_e32 v206, v206
	v_exp_f32_e32 v207, v207
	v_pk_add_f32 v[200:201], v[200:201], s[100:101] op_sel_hi:[1,0]
	v_pk_add_f32 v[202:203], v[202:203], s[100:101] op_sel_hi:[1,0]
	v_pk_add_f32 v[204:205], v[204:205], s[100:101] op_sel_hi:[1,0]
	v_pk_add_f32 v[206:207], v[206:207], s[100:101] op_sel_hi:[1,0]
	v_rcp_f32_e32 v200, v200
	v_rcp_f32_e32 v201, v201
	v_rcp_f32_e32 v202, v202
	v_rcp_f32_e32 v203, v203
	v_rcp_f32_e32 v204, v204
	v_rcp_f32_e32 v205, v205
	v_rcp_f32_e32 v206, v206
	v_rcp_f32_e32 v207, v207
	v_pk_mul_f32 v[200:201], v[18:19], v[200:201]
	v_pk_mul_f32 v[202:203], v[20:21], v[202:203]
	v_pk_mul_f32 v[204:205], v[22:23], v[204:205]
	v_pk_mul_f32 v[206:207], v[24:25], v[206:207]
	v_mov_b32_e32 v36, v42
	v_cvt_pk_bf16_f32 v18, v204, v205
	v_cvt_pk_bf16_f32 v19, v206, v207
	v_cvt_pk_bf16_f32 v20, v200, v201
	v_cvt_pk_bf16_f32 v21, v202, v203
	s_mov_b64 s[72:73], -1
	global_store_dwordx4 v[26:27], v[18:21], off offset:256
	v_pk_mul_f32 v[200:201], v[10:11], s[98:99] op_sel_hi:[1,0]
	v_pk_mul_f32 v[202:203], v[12:13], s[98:99] op_sel_hi:[1,0]
	v_pk_mul_f32 v[204:205], v[14:15], s[98:99] op_sel_hi:[1,0]
	v_pk_mul_f32 v[206:207], v[16:17], s[98:99] op_sel_hi:[1,0]
	v_exp_f32_e32 v200, v200
	v_exp_f32_e32 v201, v201
	v_exp_f32_e32 v202, v202
	v_exp_f32_e32 v203, v203
	v_exp_f32_e32 v204, v204
	v_exp_f32_e32 v205, v205
	v_exp_f32_e32 v206, v206
	v_exp_f32_e32 v207, v207
	v_pk_add_f32 v[200:201], v[200:201], s[100:101] op_sel_hi:[1,0]
	v_pk_add_f32 v[202:203], v[202:203], s[100:101] op_sel_hi:[1,0]
	v_pk_add_f32 v[204:205], v[204:205], s[100:101] op_sel_hi:[1,0]
	v_pk_add_f32 v[206:207], v[206:207], s[100:101] op_sel_hi:[1,0]
	v_rcp_f32_e32 v200, v200
	v_rcp_f32_e32 v201, v201
	v_rcp_f32_e32 v202, v202
	v_rcp_f32_e32 v203, v203
	v_rcp_f32_e32 v204, v204
	v_rcp_f32_e32 v205, v205
	v_rcp_f32_e32 v206, v206
	v_rcp_f32_e32 v207, v207
	v_pk_mul_f32 v[200:201], v[10:11], v[200:201]
	v_pk_mul_f32 v[202:203], v[12:13], v[202:203]
	v_pk_mul_f32 v[204:205], v[14:15], v[204:205]
	v_pk_mul_f32 v[206:207], v[16:17], v[206:207]
	v_mov_b32_e32 v26, v36
	v_add_u32_e32 v10, 0xb0, v161
	v_mad_i64_i32 v[10:11], s[70:71], s70, v10, 0
	v_lshl_add_u64 v[10:11], v[10:11], 1, v[122:123]
	v_cvt_pk_bf16_f32 v12, v204, v205
	v_cvt_pk_bf16_f32 v13, v206, v207
	v_cvt_pk_bf16_f32 v14, v200, v201
	v_cvt_pk_bf16_f32 v15, v202, v203
	s_mov_b64 s[8:9], -1
	global_store_dwordx4 v[10:11], v[12:15], off
	v_pk_mul_f32 v[200:201], v[2:3], s[98:99] op_sel_hi:[1,0]
	v_pk_mul_f32 v[202:203], v[4:5], s[98:99] op_sel_hi:[1,0]
	v_pk_mul_f32 v[204:205], v[6:7], s[98:99] op_sel_hi:[1,0]
	v_pk_mul_f32 v[206:207], v[8:9], s[98:99] op_sel_hi:[1,0]
	v_exp_f32_e32 v200, v200
	v_exp_f32_e32 v201, v201
	v_exp_f32_e32 v202, v202
	v_exp_f32_e32 v203, v203
	v_exp_f32_e32 v204, v204
	v_exp_f32_e32 v205, v205
	v_exp_f32_e32 v206, v206
	v_exp_f32_e32 v207, v207
	v_pk_add_f32 v[200:201], v[200:201], s[100:101] op_sel_hi:[1,0]
	v_pk_add_f32 v[202:203], v[202:203], s[100:101] op_sel_hi:[1,0]
	v_pk_add_f32 v[204:205], v[204:205], s[100:101] op_sel_hi:[1,0]
	v_pk_add_f32 v[206:207], v[206:207], s[100:101] op_sel_hi:[1,0]
	v_rcp_f32_e32 v200, v200
	v_rcp_f32_e32 v201, v201
	v_rcp_f32_e32 v202, v202
	v_rcp_f32_e32 v203, v203
	v_rcp_f32_e32 v204, v204
	v_rcp_f32_e32 v205, v205
	v_rcp_f32_e32 v206, v206
	v_rcp_f32_e32 v207, v207
	v_pk_mul_f32 v[200:201], v[2:3], v[200:201]
	v_pk_mul_f32 v[202:203], v[4:5], v[202:203]
	v_pk_mul_f32 v[204:205], v[6:7], v[204:205]
	v_pk_mul_f32 v[206:207], v[8:9], v[206:207]
	v_mov_b32_e32 v20, v26
	s_and_b64 vcc, exec, s[54:55]
	v_cvt_pk_bf16_f32 v2, v204, v205
	v_cvt_pk_bf16_f32 v3, v206, v207
	v_cvt_pk_bf16_f32 v4, v200, v201
	v_cvt_pk_bf16_f32 v5, v202, v203
	global_store_dwordx4 v[10:11], v[2:5], off offset:256
	s_branch .LBB0_416
.Lmy_e1_act2:
	s_mov_b32 s98, 0xbfb8aa3b
	s_mov_b32 s100, 1.0
	s_xor_b64 s[74:75], s[74:75], -1
	s_xor_b64 s[76:77], s[76:77], -1
	v_pk_mul_f32 v[200:201], v[122:123], s[98:99] op_sel_hi:[1,0]
	v_pk_mul_f32 v[202:203], v[124:125], s[98:99] op_sel_hi:[1,0]
	v_pk_mul_f32 v[204:205], v[126:127], s[98:99] op_sel_hi:[1,0]
	v_pk_mul_f32 v[206:207], v[128:129], s[98:99] op_sel_hi:[1,0]
	v_exp_f32_e32 v200, v200
	v_exp_f32_e32 v201, v201
	v_exp_f32_e32 v202, v202
	v_exp_f32_e32 v203, v203
	v_exp_f32_e32 v204, v204
	v_exp_f32_e32 v205, v205
	v_exp_f32_e32 v206, v206
	v_exp_f32_e32 v207, v207
	v_pk_add_f32 v[200:201], v[200:201], s[100:101] op_sel_hi:[1,0]
	v_pk_add_f32 v[202:203], v[202:203], s[100:101] op_sel_hi:[1,0]
	v_pk_add_f32 v[204:205], v[204:205], s[100:101] op_sel_hi:[1,0]
	v_pk_add_f32 v[206:207], v[206:207], s[100:101] op_sel_hi:[1,0]
	v_rcp_f32_e32 v200, v200
	v_rcp_f32_e32 v201, v201
	v_rcp_f32_e32 v202, v202
	v_rcp_f32_e32 v203, v203
	v_rcp_f32_e32 v204, v204
	v_rcp_f32_e32 v205, v205
	v_rcp_f32_e32 v206, v206
	v_rcp_f32_e32 v207, v207
	v_mov_b32_e32 v162, 0
	s_mov_b64 s[78:79], 0
	s_lshl_b32 s6, s6, 8
	s_add_i32 s6, s7, s6
	v_or_b32_e32 v122, s6, v156
	s_lshl_b32 s6, s72, 1
	s_add_u32 s6, s38, s6
	v_lshl_add_u32 v161, s8, 8, v154
	s_addc_u32 s7, s39, 0
	v_ashrrev_i32_e32 v123, 31, v122
	v_lshl_add_u64 v[122:123], v[122:123], 1, s[6:7]
	v_mad_i64_i32 v[124:125], s[6:7], s70, v161, 0
	v_lshl_add_u64 v[124:125], v[124:125], 1, v[122:123]
	v_cvt_pk_bf16_f32 v126, v204, v205
	v_cvt_pk_bf16_f32 v127, v206, v207
	v_cvt_pk_bf16_f32 v128, v200, v201
	v_cvt_pk_bf16_f32 v129, v202, v203
	global_store_dwordx4 v[124:125], v[126:129], off
	v_pk_mul_f32 v[200:201], v[114:115], s[98:99] op_sel_hi:[1,0]
	v_pk_mul_f32 v[202:203], v[116:117], s[98:99] op_sel_hi:[1,0]
	v_pk_mul_f32 v[204:205], v[118:119], s[98:99] op_sel_hi:[1,0]
	v_pk_mul_f32 v[206:207], v[120:121], s[98:99] op_sel_hi:[1,0]
	v_exp_f32_e32 v200, v200
	v_exp_f32_e32 v201, v201
	v_exp_f32_e32 v202, v202
	v_exp_f32_e32 v203, v203
	v_exp_f32_e32 v204, v204
	v_exp_f32_e32 v205, v205
	v_exp_f32_e32 v206, v206
	v_exp_f32_e32 v207, v207
	v_pk_add_f32 v[200:201], v[200:201], s[100:101] op_sel_hi:[1,0]
	v_pk_add_f32 v[202:203], v[202:203], s[100:101] op_sel_hi:[1,0]
	v_pk_add_f32 v[204:205], v[204:205], s[100:101] op_sel_hi:[1,0]
	v_pk_add_f32 v[206:207], v[206:207], s[100:101] op_sel_hi:[1,0]
	v_rcp_f32_e32 v200, v200
	v_rcp_f32_e32 v201, v201
	v_rcp_f32_e32 v202, v202
	v_rcp_f32_e32 v203, v203
	v_rcp_f32_e32 v204, v204
	v_rcp_f32_e32 v205, v205
	v_rcp_f32_e32 v206, v206
	v_rcp_f32_e32 v207, v207
	v_mov_b32_e32 v150, v162
	v_cvt_pk_bf16_f32 v114, v204, v205
	v_cvt_pk_bf16_f32 v115, v206, v207
	v_cvt_pk_bf16_f32 v116, v200, v201
	v_cvt_pk_bf16_f32 v117, v202, v203
	global_store_dwordx4 v[124:125], v[114:117], off offset:256
	v_pk_mul_f32 v[200:201], v[106:107], s[98:99] op_sel_hi:[1,0]
	v_pk_mul_f32 v[202:203], v[108:109], s[98:99] op_sel_hi:[1,0]
	v_pk_mul_f32 v[204:205], v[110:111], s[98:99] op_sel_hi:[1,0]
	v_pk_mul_f32 v[206:207], v[112:113], s[98:99] op_sel_hi:[1,0]
	v_exp_f32_e32 v200, v200
	v_exp_f32_e32 v201, v201
	v_exp_f32_e32 v202, v202
	v_exp_f32_e32 v203, v203
	v_exp_f32_e32 v204, v204
	v_exp_f32_e32 v205, v205
	v_exp_f32_e32 v206, v206
	v_exp_f32_e32 v207, v207
	v_pk_add_f32 v[200:201], v[200:201], s[100:101] op_sel_hi:[1,0]
	v_pk_add_f32 v[202:203], v[202:203], s[100:101] op_sel_hi:[1,0]
	v_pk_add_f32 v[204:205], v[204:205], s[100:101] op_sel_hi:[1,0]
	v_pk_add_f32 v[206:207], v[206:207], s[100:101] op_sel_hi:[1,0]
	v_rcp_f32_e32 v200, v200
	v_rcp_f32_e32 v201, v201
	v_rcp_f32_e32 v202, v202
	v_rcp_f32_e32 v203, v203
	v_rcp_f32_e32 v204, v204
	v_rcp_f32_e32 v205, v205
	v_rcp_f32_e32 v206, v206
	v_rcp_f32_e32 v207, v207
	v_mov_b32_e32 v124, v150
	v_or_b32_e32 v106, 16, v161
	v_mad_i64_i32 v[106:107], s[72:73], s70, v106, 0
	v_lshl_add_u64 v[106:107], v[106:107], 1, v[122:123]
	v_cvt_pk_bf16_f32 v108, v204, v205
	v_cvt_pk_bf16_f32 v109, v206, v207
	v_cvt_pk_bf16_f32 v110, v200, v201
	v_cvt_pk_bf16_f32 v111, v202, v203
	global_store_dwordx4 v[106:107], v[108:111], off
	v_pk_mul_f32 v[200:201], v[98:99], s[98:99] op_sel_hi:[1,0]
	v_pk_mul_f32 v[202:203], v[100:101], s[98:99] op_sel_hi:[1,0]
	v_pk_mul_f32 v[204:205], v[102:103], s[98:99] op_sel_hi:[1,0]
	v_pk_mul_f32 v[206:207], v[104:105], s[98:99] op_sel_hi:[1,0]
	v_exp_f32_e32 v200, v200
	v_exp_f32_e32 v201, v201
	v_exp_f32_e32 v202, v202
	v_exp_f32_e32 v203, v203
	v_exp_f32_e32 v204, v204
	v_exp_f32_e32 v205, v205
	v_exp_f32_e32 v206, v206
	v_exp_f32_e32 v207, v207
	v_pk_add_f32 v[200:201], v[200:201], s[100:101] op_sel_hi:[1,0]
	v_pk_add_f32 v[202:203], v[202:203], s[100:101] op_sel_hi:[1,0]
	v_pk_add_f32 v[204:205], v[204:205], s[100:101] op_sel_hi:[1,0]
	v_pk_add_f32 v[206:207], v[206:207], s[100:101] op_sel_hi:[1,0]
	v_rcp_f32_e32 v200, v200
	v_rcp_f32_e32 v201, v201
	v_rcp_f32_e32 v202, v202
	v_rcp_f32_e32 v203, v203
	v_rcp_f32_e32 v204, v204
	v_rcp_f32_e32 v205, v205
	v_rcp_f32_e32 v206, v206
	v_rcp_f32_e32 v207, v207
	v_mov_b32_e32 v116, v124
	v_cvt_pk_bf16_f32 v98, v204, v205
	v_cvt_pk_bf16_f32 v99, v206, v207
	v_cvt_pk_bf16_f32 v100, v200, v201
	v_cvt_pk_bf16_f32 v101, v202, v203
	global_store_dwordx4 v[106:107], v[98:101], off offset:256
	v_pk_mul_f32 v[200:201], v[90:91], s[98:99] op_sel_hi:[1,0]
	v_pk_mul_f32 v[202:203], v[92:93], s[98:99] op_sel_hi:[1,0]
	v_pk_mul_f32 v[204:205], v[94:95], s[98:99] op_sel_hi:[1,0]
	v_pk_mul_f32 v[206:207], v[96:97], s[98:99] op_sel_hi:[1,0]
	v_exp_f32_e32 v200, v200
	v_exp_f32_e32 v201, v201
	v_exp_f32_e32 v202, v202
	v_exp_f32_e32 v203, v203
	v_exp_f32_e32 v204, v204
	v_exp_f32_e32 v205, v205
	v_exp_f32_e32 v206, v206
	v_exp_f32_e32 v207, v207
	v_pk_add_f32 v[200:201], v[200:201], s[100:101] op_sel_hi:[1,0]
	v_pk_add_f32 v[202:203], v[202:203], s[100:101] op_sel_hi:[1,0]
	v_pk_add_f32 v[204:205], v[204:205], s[100:101] op_sel_hi:[1,0]
	v_pk_add_f32 v[206:207], v[206:207], s[100:101] op_sel_hi:[1,0]
	v_rcp_f32_e32 v200, v200
	v_rcp_f32_e32 v201, v201
	v_rcp_f32_e32 v202, v202
	v_rcp_f32_e32 v203, v203
	v_rcp_f32_e32 v204, v204
	v_rcp_f32_e32 v205, v205
	v_rcp_f32_e32 v206, v206
	v_rcp_f32_e32 v207, v207
	v_mov_b32_e32 v106, v116
	v_or_b32_e32 v90, 32, v161
	v_mad_i64_i32 v[90:91], s[72:73], s70, v90, 0
	v_lshl_add_u64 v[90:91], v[90:91], 1, v[122:123]
	v_cvt_pk_bf16_f32 v92, v204, v205
	v_cvt_pk_bf16_f32 v93, v206, v207
	v_cvt_pk_bf16_f32 v94, v200, v201
	v_cvt_pk_bf16_f32 v95, v202, v203
	global_store_dwordx4 v[90:91], v[92:95], off
	v_pk_mul_f32 v[200:201], v[82:83], s[98:99] op_sel_hi:[1,0]
	v_pk_mul_f32 v[202:203], v[84:85], s[98:99] op_sel_hi:[1,0]
	v_pk_mul_f32 v[204:205], v[86:87], s[98:99] op_sel_hi:[1,0]
	v_pk_mul_f32 v[206:207], v[88:89], s[98:99] op_sel_hi:[1,0]
	v_exp_f32_e32 v200, v200
	v_exp_f32_e32 v201, v201
	v_exp_f32_e32 v202, v202
	v_exp_f32_e32 v203, v203
	v_exp_f32_e32 v204, v204
	v_exp_f32_e32 v205, v205
	v_exp_f32_e32 v206, v206
	v_exp_f32_e32 v207, v207
	v_pk_add_f32 v[200:201], v[200:201], s[100:101] op_sel_hi:[1,0]
	v_pk_add_f32 v[202:203], v[202:203], s[100:101] op_sel_hi:[1,0]
	v_pk_add_f32 v[204:205], v[204:205], s[100:101] op_sel_hi:[1,0]
	v_pk_add_f32 v[206:207], v[206:207], s[100:101] op_sel_hi:[1,0]
	v_rcp_f32_e32 v200, v200
	v_rcp_f32_e32 v201, v201
	v_rcp_f32_e32 v202, v202
	v_rcp_f32_e32 v203, v203
	v_rcp_f32_e32 v204, v204
	v_rcp_f32_e32 v205, v205
	v_rcp_f32_e32 v206, v206
	v_rcp_f32_e32 v207, v207
	v_mov_b32_e32 v100, v106
	v_cvt_pk_bf16_f32 v82, v204, v205
	v_cvt_pk_bf16_f32 v83, v206, v207
	v_cvt_pk_bf16_f32 v84, v200, v201
	v_cvt_pk_bf16_f32 v85, v202, v203
	global_store_dwordx4 v[90:91], v[82:85], off offset:256
	v_pk_mul_f32 v[200:201], v[74:75], s[98:99] op_sel_hi:[1,0]
	v_pk_mul_f32 v[202:203], v[76:77], s[98:99] op_sel_hi:[1,0]
	v_pk_mul_f32 v[204:205], v[78:79], s[98:99] op_sel_hi:[1,0]
	v_pk_mul_f32 v[206:207], v[80:81], s[98:99] op_sel_hi:[1,0]
	v_exp_f32_e32 v200, v200
	v_exp_f32_e32 v201, v201
	v_exp_f32_e32 v202, v202
	v_exp_f32_e32 v203, v203
	v_exp_f32_e32 v204, v204
	v_exp_f32_e32 v205, v205
	v_exp_f32_e32 v206, v206
	v_exp_f32_e32 v207, v207
	v_pk_add_f32 v[200:201], v[200:201], s[100:101] op_sel_hi:[1,0]
	v_pk_add_f32 v[202:203], v[202:203], s[100:101] op_sel_hi:[1,0]
	v_pk_add_f32 v[204:205], v[204:205], s[100:101] op_sel_hi:[1,0]
	v_pk_add_f32 v[206:207], v[206:207], s[100:101] op_sel_hi:[1,0]
	v_rcp_f32_e32 v200, v200
	v_rcp_f32_e32 v201, v201
	v_rcp_f32_e32 v202, v202
	v_rcp_f32_e32 v203, v203
	v_rcp_f32_e32 v204, v204
	v_rcp_f32_e32 v205, v205
	v_rcp_f32_e32 v206, v206
	v_rcp_f32_e32 v207, v207
	v_mov_b32_e32 v90, v100
	v_or_b32_e32 v74, 48, v161
	v_mad_i64_i32 v[74:75], s[72:73], s70, v74, 0
	v_lshl_add_u64 v[74:75], v[74:75], 1, v[122:123]
	v_cvt_pk_bf16_f32 v76, v204, v205
	v_cvt_pk_bf16_f32 v77, v206, v207
	v_cvt_pk_bf16_f32 v78, v200, v201
	v_cvt_pk_bf16_f32 v79, v202, v203
	global_store_dwordx4 v[74:75], v[76:79], off
	v_pk_mul_f32 v[200:201], v[66:67], s[98:99] op_sel_hi:[1,0]
	v_pk_mul_f32 v[202:203], v[68:69], s[98:99] op_sel_hi:[1,0]
	v_pk_mul_f32 v[204:205], v[70:71], s[98:99] op_sel_hi:[1,0]
	v_pk_mul_f32 v[206:207], v[72:73], s[98:99] op_sel_hi:[1,0]
	v_exp_f32_e32 v200, v200
	v_exp_f32_e32 v201, v201
	v_exp_f32_e32 v202, v202
	v_exp_f32_e32 v203, v203
	v_exp_f32_e32 v204, v204
	v_exp_f32_e32 v205, v205
	v_exp_f32_e32 v206, v206
	v_exp_f32_e32 v207, v207
	v_pk_add_f32 v[200:201], v[200:201], s[100:101] op_sel_hi:[1,0]
	v_pk_add_f32 v[202:203], v[202:203], s[100:101] op_sel_hi:[1,0]
	v_pk_add_f32 v[204:205], v[204:205], s[100:101] op_sel_hi:[1,0]
	v_pk_add_f32 v[206:207], v[206:207], s[100:101] op_sel_hi:[1,0]
	v_rcp_f32_e32 v200, v200
	v_rcp_f32_e32 v201, v201
	v_rcp_f32_e32 v202, v202
	v_rcp_f32_e32 v203, v203
	v_rcp_f32_e32 v204, v204
	v_rcp_f32_e32 v205, v205
	v_rcp_f32_e32 v206, v206
	v_rcp_f32_e32 v207, v207
	v_mov_b32_e32 v84, v90
	v_cvt_pk_bf16_f32 v66, v204, v205
	v_cvt_pk_bf16_f32 v67, v206, v207
	v_cvt_pk_bf16_f32 v68, v200, v201
	v_cvt_pk_bf16_f32 v69, v202, v203
	global_store_dwordx4 v[74:75], v[66:69], off offset:256
	v_pk_mul_f32 v[200:201], v[58:59], s[98:99] op_sel_hi:[1,0]
	v_pk_mul_f32 v[202:203], v[60:61], s[98:99] op_sel_hi:[1,0]
	v_pk_mul_f32 v[204:205], v[62:63], s[98:99] op_sel_hi:[1,0]
	v_pk_mul_f32 v[206:207], v[64:65], s[98:99] op_sel_hi:[1,0]
	v_exp_f32_e32 v200, v200
	v_exp_f32_e32 v201, v201
	v_exp_f32_e32 v202, v202
	v_exp_f32_e32 v203, v203
	v_exp_f32_e32 v204, v204
	v_exp_f32_e32 v205, v205
	v_exp_f32_e32 v206, v206
	v_exp_f32_e32 v207, v207
	v_pk_add_f32 v[200:201], v[200:201], s[100:101] op_sel_hi:[1,0]
	v_pk_add_f32 v[202:203], v[202:203], s[100:101] op_sel_hi:[1,0]
	v_pk_add_f32 v[204:205], v[204:205], s[100:101] op_sel_hi:[1,0]
	v_pk_add_f32 v[206:207], v[206:207], s[100:101] op_sel_hi:[1,0]
	v_rcp_f32_e32 v200, v200
	v_rcp_f32_e32 v201, v201
	v_rcp_f32_e32 v202, v202
	v_rcp_f32_e32 v203, v203
	v_rcp_f32_e32 v204, v204
	v_rcp_f32_e32 v205, v205
	v_rcp_f32_e32 v206, v206
	v_rcp_f32_e32 v207, v207
	v_mov_b32_e32 v74, v84
	v_add_u32_e32 v58, 0x80, v161
	v_mad_i64_i32 v[58:59], s[72:73], s70, v58, 0
	v_lshl_add_u64 v[58:59], v[58:59], 1, v[122:123]
	v_cvt_pk_bf16_f32 v60, v204, v205
	v_cvt_pk_bf16_f32 v61, v206, v207
	v_cvt_pk_bf16_f32 v62, v200, v201
	v_cvt_pk_bf16_f32 v63, v202, v203
	global_store_dwordx4 v[58:59], v[60:63], off
	v_pk_mul_f32 v[200:201], v[50:51], s[98:99] op_sel_hi:[1,0]
	v_pk_mul_f32 v[202:203], v[52:53], s[98:99] op_sel_hi:[1,0]
	v_pk_mul_f32 v[204:205], v[54:55], s[98:99] op_sel_hi:[1,0]
	v_pk_mul_f32 v[206:207], v[56:57], s[98:99] op_sel_hi:[1,0]
	v_exp_f32_e32 v200, v200
	v_exp_f32_e32 v201, v201
	v_exp_f32_e32 v202, v202
	v_exp_f32_e32 v203, v203
	v_exp_f32_e32 v204, v204
	v_exp_f32_e32 v205, v205
	v_exp_f32_e32 v206, v206
	v_exp_f32_e32 v207, v207
	v_pk_add_f32 v[200:201], v[200:201], s[100:101] op_sel_hi:[1,0]
	v_pk_add_f32 v[202:203], v[202:203], s[100:101] op_sel_hi:[1,0]
	v_pk_add_f32 v[204:205], v[204:205], s[100:101] op_sel_hi:[1,0]
	v_pk_add_f32 v[206:207], v[206:207], s[100:101] op_sel_hi:[1,0]
	v_rcp_f32_e32 v200, v200
	v_rcp_f32_e32 v201, v201
	v_rcp_f32_e32 v202, v202
	v_rcp_f32_e32 v203, v203
	v_rcp_f32_e32 v204, v204
	v_rcp_f32_e32 v205, v205
	v_rcp_f32_e32 v206, v206
	v_rcp_f32_e32 v207, v207
	v_mov_b32_e32 v68, v74
	v_cvt_pk_bf16_f32 v50, v204, v205
	v_cvt_pk_bf16_f32 v51, v206, v207
	v_cvt_pk_bf16_f32 v52, v200, v201
	v_cvt_pk_bf16_f32 v53, v202, v203
	global_store_dwordx4 v[58:59], v[50:53], off offset:256
	v_pk_mul_f32 v[200:201], v[42:43], s[98:99] op_sel_hi:[1,0]
	v_pk_mul_f32 v[202:203], v[44:45], s[98:99] op_sel_hi:[1,0]
	v_pk_mul_f32 v[204:205], v[46:47], s[98:99] op_sel_hi:[1,0]
	v_pk_mul_f32 v[206:207], v[48:49], s[98:99] op_sel_hi:[1,0]
	v_exp_f32_e32 v200, v200
	v_exp_f32_e32 v201, v201
	v_exp_f32_e32 v202, v202
	v_exp_f32_e32 v203, v203
	v_exp_f32_e32 v204, v204
	v_exp_f32_e32 v205, v205
	v_exp_f32_e32 v206, v206
	v_exp_f32_e32 v207, v207
	v_pk_add_f32 v[200:201], v[200:201], s[100:101] op_sel_hi:[1,0]
	v_pk_add_f32 v[202:203], v[202:203], s[100:101] op_sel_hi:[1,0]
	v_pk_add_f32 v[204:205], v[204:205], s[100:101] op_sel_hi:[1,0]
	v_pk_add_f32 v[206:207], v[206:207], s[100:101] op_sel_hi:[1,0]
	v_rcp_f32_e32 v200, v200
	v_rcp_f32_e32 v201, v201
	v_rcp_f32_e32 v202, v202
	v_rcp_f32_e32 v203, v203
	v_rcp_f32_e32 v204, v204
	v_rcp_f32_e32 v205, v205
	v_rcp_f32_e32 v206, v206
	v_rcp_f32_e32 v207, v207
	v_mov_b32_e32 v58, v68
	v_add_u32_e32 v42, 0x90, v161
	v_mad_i64_i32 v[42:43], s[72:73], s70, v42, 0
	v_lshl_add_u64 v[42:43], v[42:43], 1, v[122:123]
	v_cvt_pk_bf16_f32 v44, v204, v205
	v_cvt_pk_bf16_f32 v45, v206, v207
	v_cvt_pk_bf16_f32 v46, v200, v201
	v_cvt_pk_bf16_f32 v47, v202, v203
	global_store_dwordx4 v[42:43], v[44:47], off
	v_pk_mul_f32 v[200:201], v[34:35], s[98:99] op_sel_hi:[1,0]
	v_pk_mul_f32 v[202:203], v[36:37], s[98:99] op_sel_hi:[1,0]
	v_pk_mul_f32 v[204:205], v[38:39], s[98:99] op_sel_hi:[1,0]
	v_pk_mul_f32 v[206:207], v[40:41], s[98:99] op_sel_hi:[1,0]
	v_exp_f32_e32 v200, v200
	v_exp_f32_e32 v201, v201
	v_exp_f32_e32 v202, v202
	v_exp_f32_e32 v203, v203
	v_exp_f32_e32 v204, v204
	v_exp_f32_e32 v205, v205
	v_exp_f32_e32 v206, v206
	v_exp_f32_e32 v207, v207
	v_pk_add_f32 v[200:201], v[200:201], s[100:101] op_sel_hi:[1,0]
	v_pk_add_f32 v[202:203], v[202:203], s[100:101] op_sel_hi:[1,0]
	v_pk_add_f32 v[204:205], v[204:205], s[100:101] op_sel_hi:[1,0]
	v_pk_add_f32 v[206:207], v[206:207], s[100:101] op_sel_hi:[1,0]
	v_rcp_f32_e32 v200, v200
	v_rcp_f32_e32 v201, v201
	v_rcp_f32_e32 v202, v202
	v_rcp_f32_e32 v203, v203
	v_rcp_f32_e32 v204, v204
	v_rcp_f32_e32 v205, v205
	v_rcp_f32_e32 v206, v206
	v_rcp_f32_e32 v207, v207
	v_mov_b32_e32 v52, v58
	v_cvt_pk_bf16_f32 v34, v204, v205
	v_cvt_pk_bf16_f32 v35, v206, v207
	v_cvt_pk_bf16_f32 v36, v200, v201
	v_cvt_pk_bf16_f32 v37, v202, v203
	global_store_dwordx4 v[42:43], v[34:37], off offset:256
	v_pk_mul_f32 v[200:201], v[26:27], s[98:99] op_sel_hi:[1,0]
	v_pk_mul_f32 v[202:203], v[28:29], s[98:99] op_sel_hi:[1,0]
	v_pk_mul_f32 v[204:205], v[30:31], s[98:99] op_sel_hi:[1,0]
	v_pk_mul_f32 v[206:207], v[32:33], s[98:99] op_sel_hi:[1,0]
	v_exp_f32_e32 v200, v200
	v_exp_f32_e32 v201, v201
	v_exp_f32_e32 v202, v202
	v_exp_f32_e32 v203, v203
	v_exp_f32_e32 v204, v204
	v_exp_f32_e32 v205, v205
	v_exp_f32_e32 v206, v206
	v_exp_f32_e32 v207, v207
	v_pk_add_f32 v[200:201], v[200:201], s[100:101] op_sel_hi:[1,0]
	v_pk_add_f32 v[202:203], v[202:203], s[100:101] op_sel_hi:[1,0]
	v_pk_add_f32 v[204:205], v[204:205], s[100:101] op_sel_hi:[1,0]
	v_pk_add_f32 v[206:207], v[206:207], s[100:101] op_sel_hi:[1,0]
	v_rcp_f32_e32 v200, v200
	v_rcp_f32_e32 v201, v201
	v_rcp_f32_e32 v202, v202
	v_rcp_f32_e32 v203, v203
	v_rcp_f32_e32 v204, v204
	v_rcp_f32_e32 v205, v205
	v_rcp_f32_e32 v206, v206
	v_rcp_f32_e32 v207, v207
	v_mov_b32_e32 v42, v52
	v_add_u32_e32 v26, 0xa0, v161
	v_mad_i64_i32 v[26:27], s[72:73], s70, v26, 0
	v_lshl_add_u64 v[26:27], v[26:27], 1, v[122:123]
	v_cvt_pk_bf16_f32 v28, v204, v205
	v_cvt_pk_bf16_f32 v29, v206, v207
	v_cvt_pk_bf16_f32 v30, v200, v201
	v_cvt_pk_bf16_f32 v31, v202, v203
	global_store_dwordx4 v[26:27], v[28:31], off
	v_pk_mul_f32 v[200:201], v[18:19], s[98:99] op_sel_hi:[1,0]
	v_pk_mul_f32 v[202:203], v[20:21], s[98:99] op_sel_hi:[1,0]
	v_pk_mul_f32 v[204:205], v[22:23], s[98:99] op_sel_hi:[1,0]
	v_pk_mul_f32 v[206:207], v[24:25], s[98:99] op_sel_hi:[1,0]
	v_exp_f32_e32 v200, v200
	v_exp_f32_e32 v201, v201
	v_exp_f32_e32 v202, v202
	v_exp_f32_e32 v203, v203
	v_exp_f32_e32 v204, v204
	v_exp_f32_e32 v205, v205
	v_exp_f32_e32 v206, v206
	v_exp_f32_e32 v207, v207
	v_pk_add_f32 v[200:201], v[200:201], s[100:101] op_sel_hi:[1,0]
	v_pk_add_f32 v[202:203], v[202:203], s[100:101] op_sel_hi:[1,0]
	v_pk_add_f32 v[204:205], v[204:205], s[100:101] op_sel_hi:[1,0]
	v_pk_add_f32 v[206:207], v[206:207], s[100:101] op_sel_hi:[1,0]
	v_rcp_f32_e32 v200, v200
	v_rcp_f32_e32 v201, v201
	v_rcp_f32_e32 v202, v202
	v_rcp_f32_e32 v203, v203
	v_rcp_f32_e32 v204, v204
	v_rcp_f32_e32 v205, v205
	v_rcp_f32_e32 v206, v206
	v_rcp_f32_e32 v207, v207
	v_mov_b32_e32 v36, v42
	v_cvt_pk_bf16_f32 v18, v204, v205
	v_cvt_pk_bf16_f32 v19, v206, v207
	v_cvt_pk_bf16_f32 v20, v200, v201
	v_cvt_pk_bf16_f32 v21, v202, v203
	global_store_dwordx4 v[26:27], v[18:21], off offset:256
	v_pk_mul_f32 v[200:201], v[10:11], s[98:99] op_sel_hi:[1,0]
	v_pk_mul_f32 v[202:203], v[12:13], s[98:99] op_sel_hi:[1,0]
	v_pk_mul_f32 v[204:205], v[14:15], s[98:99] op_sel_hi:[1,0]
	v_pk_mul_f32 v[206:207], v[16:17], s[98:99] op_sel_hi:[1,0]
	v_exp_f32_e32 v200, v200
	v_exp_f32_e32 v201, v201
	v_exp_f32_e32 v202, v202
	v_exp_f32_e32 v203, v203
	v_exp_f32_e32 v204, v204
	v_exp_f32_e32 v205, v205
	v_exp_f32_e32 v206, v206
	v_exp_f32_e32 v207, v207
	v_pk_add_f32 v[200:201], v[200:201], s[100:101] op_sel_hi:[1,0]
	v_pk_add_f32 v[202:203], v[202:203], s[100:101] op_sel_hi:[1,0]
	v_pk_add_f32 v[204:205], v[204:205], s[100:101] op_sel_hi:[1,0]
	v_pk_add_f32 v[206:207], v[206:207], s[100:101] op_sel_hi:[1,0]
	v_rcp_f32_e32 v200, v200
	v_rcp_f32_e32 v201, v201
	v_rcp_f32_e32 v202, v202
	v_rcp_f32_e32 v203, v203
	v_rcp_f32_e32 v204, v204
	v_rcp_f32_e32 v205, v205
	v_rcp_f32_e32 v206, v206
	v_rcp_f32_e32 v207, v207
	v_mov_b32_e32 v26, v36
	s_mov_b64 s[72:73], 0
	v_add_u32_e32 v10, 0xb0, v161
	v_mad_i64_i32 v[10:11], s[70:71], s70, v10, 0
	v_lshl_add_u64 v[10:11], v[10:11], 1, v[122:123]
	v_cvt_pk_bf16_f32 v12, v204, v205
	v_cvt_pk_bf16_f32 v13, v206, v207
	v_cvt_pk_bf16_f32 v14, v200, v201
	v_cvt_pk_bf16_f32 v15, v202, v203
	global_store_dwordx4 v[10:11], v[12:15], off
	s_mov_b64 s[6:7], -1
	v_pk_mul_f32 v[200:201], v[2:3], s[98:99] op_sel_hi:[1,0]
	v_pk_mul_f32 v[202:203], v[4:5], s[98:99] op_sel_hi:[1,0]
	v_pk_mul_f32 v[204:205], v[6:7], s[98:99] op_sel_hi:[1,0]
	v_pk_mul_f32 v[206:207], v[8:9], s[98:99] op_sel_hi:[1,0]
	v_exp_f32_e32 v200, v200
	v_exp_f32_e32 v201, v201
	v_exp_f32_e32 v202, v202
	v_exp_f32_e32 v203, v203
	v_exp_f32_e32 v204, v204
	v_exp_f32_e32 v205, v205
	v_exp_f32_e32 v206, v206
	v_exp_f32_e32 v207, v207
	v_pk_add_f32 v[200:201], v[200:201], s[100:101] op_sel_hi:[1,0]
	v_pk_add_f32 v[202:203], v[202:203], s[100:101] op_sel_hi:[1,0]
	v_pk_add_f32 v[204:205], v[204:205], s[100:101] op_sel_hi:[1,0]
	v_pk_add_f32 v[206:207], v[206:207], s[100:101] op_sel_hi:[1,0]
	v_rcp_f32_e32 v200, v200
	v_rcp_f32_e32 v201, v201
	v_rcp_f32_e32 v202, v202
	v_rcp_f32_e32 v203, v203
	v_rcp_f32_e32 v204, v204
	v_rcp_f32_e32 v205, v205
	v_rcp_f32_e32 v206, v206
	v_rcp_f32_e32 v207, v207
	v_mov_b32_e32 v20, v26
	s_mov_b64 s[8:9], 0
	s_and_b64 vcc, exec, s[54:55]
	v_cvt_pk_bf16_f32 v2, v204, v205
	v_cvt_pk_bf16_f32 v3, v206, v207
	v_cvt_pk_bf16_f32 v4, v200, v201
	v_cvt_pk_bf16_f32 v5, v202, v203
	global_store_dwordx4 v[10:11], v[2:5], off offset:256
	s_branch .LBB0_416
